# speedup vs baseline: 1.1180x; 1.0290x over previous
; DEV int tidx() { int t = threadIdx.x; asm volatile("" : "+v"(t)); return t; }
; #define ctr ((int*)(wsp(p) + W_CTR))
; DEV void phase_attn(const Params& p, int* ctr, char* smem) {
;   int* sitem = (int*)(smem + 78848);
;   for (;;) {
;     __syncthreads();
;     if (tidx() == 0) *sitem = atomicAdd(ctr, 1);
;     __syncthreads();
;     const int item = __builtin_amdgcn_readfirstlane(*sitem);
;     if (item >= 64 + 2048) break;
.LBB0_439:
	s_or_b64 exec, exec, s[0:1]
	v_readlane_b32 s2, v254, 58
	s_mov_b64 s[0:1], s[62:63]
	s_lshl_b32 s92, s2, 1
	s_barrier
	s_lshl_b64 s[2:3], s[92:93], 2
	s_add_u32 s0, s0, s2
	v_writelane_b32 v255, s2, 30
	s_addc_u32 s1, s1, s3
	s_add_u32 s12, s0, 0x2720000
	s_mov_b32 s41, s93
	v_writelane_b32 v255, s3, 31
	s_addc_u32 s13, s1, 0
	s_mul_i32 s2, s92, 12
	s_and_b32 s3, s52, 7
	s_lshl_b32 s3, s3, 2
	s_add_i32 s2, s2, s3
	s_addk_i32 s2, 32
	s_add_u32 s12, s12, s2
	s_addc_u32 s13, s13, 0
	s_branch .LBB0_443

; #define ws (wsp(p))
; template <int DQ, int DV, int NQT, bool SAMPLE>
; DEV void attn_item(const Params& p, int item, char* smem) {
;     ...
;     const int qb = 63 - (item >> 5), bh = item & 31, b = bh >> 3, h = bh & 7;
;     K1 = (const u16*)(ws + A_KN) + (size_t)(b * 8 + h) * 8192 * 128;
;     ld1 = 128;
;     K2 = (const u16*)(ws + E_KRP) + (size_t)b * 8192 * 64;
;     Vt = (const u16*)(ws + OFF_B) + (size_t)(b * 8 + h) * 8192 * 128;
;     ldv = 0;
;     nkt = 4 * qb + 4;
;     wlim = 4 * qb + 2 * (w >> 1) + 1;
; #pragma unroll
;     for (int qt = 0; qt < NQT; qt++) {
;       const int t = b * 8192 + qb * 128 + w * 16 * NQT + qt * 16 + fr;
;       qrow[qt] = (const u16*)(ws + A_Q) + (size_t)t * 1536 + h * 192;
;       orow[qt] = (u16*)(ws + OFF_C) + (size_t)t * 1024 + h * 128;
;     }
;   } else {
;     const int b = item >> 2, grp = item & 3;
;     K1 = (const u16*)(ws + D_CKC) + (size_t)b * 4128 * 256;
;     ld1 = 256;
;     K2 = (const u16*)(ws + D_KRC) + (size_t)b * 4128 * 64;
;     Vt = (const u16*)(ws + A_VTC) + (size_t)b * 130 * 256 * 32;
;     ldv = 0;
;     nkt = 129;
;     wlim = 129;
; #pragma unroll
;     for (int qt = 0; qt < NQT; qt++) {
;       const int r = w * 16 * NQT + qt * 16 + fr;
;       const int h = grp * 2 + (r >> 5), q = r & 31;
;       qrow[qt] = (const u16*)(ws + D_QL) + (size_t)(b * 32 + q) * 2560 + h * 320;
;       orow[qt] = (u16*)(ws + D_OL) + (size_t)(b * 32 + q) * 2048 + h * 256;
;     }
;   }
;   bf16x8 qf[NQT][NKS];
; #pragma unroll
;   for (int qt = 0; qt < NQT; qt++)
; #pragma unroll
;     for (int ks = 0; ks < NKS; ks++) qf[qt][ks] = *(const bf16x8*)(qrow[qt] + ks * 32 + fq * 8);
;   f32x4 o[DV / 16][NQT];
;   float mrun[NQT], lrun[NQT];
; #pragma unroll
;   for (int qt = 0; qt < NQT; qt++) {
;     mrun[qt] = -INFINITY;
;     lrun[qt] = 0.f;
; #pragma unroll
;     for (int d = 0; d < DV / 16; d++) o[d][qt] = (f32x4){0.f, 0.f, 0.f, 0.f};
;   }
;   u32x4 rk[NKC], rv[NVC];
;   auto gload = [&](int kt) {
; #pragma unroll
; DEV void phase_attn(const Params& p, int* ctr, char* smem) {
;     ...
;   for (;;) {
;     __syncthreads();
;     if (tidx() == 0) *sitem = atomicAdd(ctr, 1);
;     __syncthreads();
;     const int item = __builtin_amdgcn_readfirstlane(*sitem);
;     if (item >= 64 + 2048) break;
;     if (item < 64) attn_item<320, 256, 1, true>(p, item, smem);
;     else attn_item<192, 128, 2, false>(p, item - 64, smem);
.LBB0_447:
	s_or_b64 exec, exec, s[0:1]
	s_waitcnt lgkmcnt(0)
	s_barrier
	ds_read_b32 v0, v202
	s_mov_b64 s[0:1], -1
	s_waitcnt lgkmcnt(0)
	v_readfirstlane_b32 s16, v0
	s_and_b32 s2, s52, 7
	s_cmp_lt_u32 s16, 8
	s_cbranch_scc0 .Lat_q1
	s_lshl_b32 s2, s2, 3
	s_add_i32 s16, s16, s2
	s_branch .Lat_q3
.Lat_q1:
	s_sub_i32 s3, s16, 8
	s_cmp_lt_u32 s3, 0x100
	s_cbranch_scc1 .Lat_q2
	s_movk_i32 s16, 0x840
	s_branch .Lat_q3
.Lat_q2:
	s_lshl_b32 s2, s2, 2
	s_and_b32 s4, s3, 3
	s_add_i32 s2, s2, s4
	s_lshr_b32 s3, s3, 2
	s_lshl_b32 s3, s3, 5
	s_add_i32 s16, s2, s3
	s_addk_i32 s16, 64
.Lat_q3:
	s_cmpk_gt_i32 s16, 0x83f
	s_cbranch_scc1 .LBB0_442
	s_cmp_gt_i32 s16, 63
	s_cbranch_scc0 .LBB0_476
	s_sub_i32 s0, s16, 64
	s_lshr_b32 s1, s0, 5
	s_xor_b32 s19, s1, 63
	s_bfe_u32 s2, s16, 0x20003
	v_mov_b32_e32 v29, v157
	s_lshl_b32 s18, s0, 20
	s_lshl_b32 s0, s2, 13
	s_lshl_b32 s1, s19, 7
	s_mov_b64 s[8:9], s[62:63]
	v_and_b32_e32 v28, 15, v29
	s_and_b32 s17, s16, 7
	s_and_b32 s3, s18, 0x1f00000
	s_add_i32 s1, s1, s0
	v_ashrrev_i32_e32 v0, 1, v29
	v_and_b32_e32 v0, 0xffffffe0, v0
	v_or_b32_e32 v2, s1, v28
	s_add_u32 s0, s8, 0x2800000
	v_add_u32_e32 v152, v2, v0
	s_addc_u32 s1, s9, 0
	v_mov_b64_e32 v[2:3], s[0:1]
	v_or_b32_e32 v162, 16, v152
	v_mad_i64_i32 v[4:5], s[0:1], v152, s68, v[2:3]
	s_mov_b32 s5, s41
	s_mul_i32 s4, s17, 0x180
	v_mad_i64_i32 v[2:3], s[0:1], v162, s68, v[2:3]
	v_bfe_u32 v30, v29, 4, 2
	v_lshl_add_u64 v[4:5], v[4:5], 0, s[4:5]
	v_lshl_add_u64 v[2:3], v[2:3], 0, s[4:5]
	v_lshlrev_b32_e32 v0, 4, v30
	v_lshl_add_u64 v[4:5], v[4:5], 0, v[0:1]
	v_lshl_add_u64 v[2:3], v[2:3], 0, v[0:1]
	global_load_dwordx4 v[108:111], v[4:5], off
	global_load_dwordx4 v[96:99], v[4:5], off offset:64
	global_load_dwordx4 v[92:95], v[4:5], off offset:128
	global_load_dwordx4 v[80:83], v[4:5], off offset:192
	global_load_dwordx4 v[76:79], v[4:5], off offset:256
	global_load_dwordx4 v[68:71], v[4:5], off offset:320
	global_load_dwordx4 v[112:115], v[2:3], off
	global_load_dwordx4 v[104:107], v[2:3], off offset:64
	global_load_dwordx4 v[100:103], v[2:3], off offset:128
	global_load_dwordx4 v[88:91], v[2:3], off offset:192
	global_load_dwordx4 v[84:87], v[2:3], off offset:256
	global_load_dwordx4 v[72:75], v[2:3], off offset:320
	s_lshl_b32 s0, s2, 20
	s_add_u32 s0, s8, s0
	s_addc_u32 s1, s9, 0
	s_add_u32 s10, s0, 0x1d868000
	v_mul_hi_i32 v0, v29, s28
	s_addc_u32 s11, s1, 0
	s_lshl_b32 s20, s3, 1
	v_lshrrev_b32_e32 v2, 31, v0
	v_ashrrev_i32_e32 v0, 2, v0
	s_add_u32 s0, s8, s20
	v_add_u32_e32 v8, v0, v2
	s_addc_u32 s1, s9, 0
	v_mul_lo_u32 v0, v8, 24
	s_add_u32 s0, s0, 0x8980000
	v_sub_u32_e32 v0, v29, v0
	v_ashrrev_i32_e32 v9, 31, v8
	s_mov_b32 s21, s41
	s_addc_u32 s1, s1, 0
	v_lshlrev_b32_e32 v2, 3, v0
	v_cmp_gt_i32_e64 s[2:3], 16, v0
	v_cmp_lt_i32_e32 vcc, 15, v0
	v_lshlrev_b64 v[4:5], 7, v[8:9]
	s_and_saveexec_b64 s[4:5], vcc
	s_xor_b64 s[4:5], exec, s[4:5]
	v_lshl_add_u64 v[6:7], s[10:11], 0, v[4:5]
	v_mov_b32_e32 v3, v1
	v_lshl_add_u64 v[6:7], v[2:3], 1, v[6:7]
	v_lshl_add_u64 v[10:11], v[6:7], 0, s[50:51]
	s_or_saveexec_b64 s[4:5], s[4:5]
	v_lshlrev_b64 v[6:7], 8, v[8:9]
	v_ashrrev_i32_e32 v3, 31, v2
	s_xor_b64 exec, exec, s[4:5]
	v_lshl_add_u64 v[10:11], s[0:1], 0, v[6:7]
	v_lshl_add_u64 v[10:11], v[2:3], 1, v[10:11]
	s_or_b64 exec, exec, s[4:5]
	global_load_dwordx4 v[116:119], v[10:11], off
	v_add_u32_e32 v9, 0x100, v29
	v_mul_hi_i32 v0, v9, s28
	v_lshrrev_b32_e32 v10, 31, v0
	v_ashrrev_i32_e32 v0, 2, v0
	v_add_u32_e32 v16, v0, v10
	v_mul_lo_u32 v0, v16, 24
	v_sub_u32_e32 v0, v9, v0
	v_ashrrev_i32_e32 v17, 31, v16
	v_lshlrev_b32_e32 v10, 3, v0
	v_cmp_gt_i32_e64 s[4:5], 16, v0
	v_cmp_lt_i32_e32 vcc, 15, v0
	v_lshlrev_b64 v[12:13], 7, v[16:17]
	s_and_saveexec_b64 s[6:7], vcc
	s_xor_b64 s[6:7], exec, s[6:7]
	v_lshl_add_u64 v[14:15], s[10:11], 0, v[12:13]
	v_mov_b32_e32 v11, v1
	v_lshl_add_u64 v[14:15], v[10:11], 1, v[14:15]
	v_lshl_add_u64 v[18:19], v[14:15], 0, s[50:51]
	s_or_saveexec_b64 s[6:7], s[6:7]
	v_lshlrev_b64 v[14:15], 8, v[16:17]
	v_ashrrev_i32_e32 v11, 31, v10
	s_xor_b64 exec, exec, s[6:7]
	v_lshl_add_u64 v[18:19], s[0:1], 0, v[14:15]
	v_lshl_add_u64 v[18:19], v[10:11], 1, v[18:19]
	s_or_b64 exec, exec, s[6:7]
	global_load_dwordx4 v[120:123], v[18:19], off
	v_add_u32_e32 v0, 0x200, v29
	v_mul_hi_i32 v17, v0, s28
	v_lshrrev_b32_e32 v18, 31, v17
	v_ashrrev_i32_e32 v17, 2, v17
	v_add_u32_e32 v22, v17, v18
	v_mul_lo_u32 v17, v22, 24
	v_sub_u32_e32 v17, v0, v17
	v_ashrrev_i32_e32 v23, 31, v22
	v_lshlrev_b32_e32 v0, 3, v17
	v_cmp_gt_i32_e64 s[6:7], 16, v17
	v_cmp_lt_i32_e32 vcc, 15, v17
	v_lshlrev_b64 v[20:21], 7, v[22:23]
	v_lshlrev_b64 v[18:19], 8, v[22:23]
	s_and_saveexec_b64 s[14:15], vcc
	s_xor_b64 s[14:15], exec, s[14:15]
	v_lshlrev_b64 v[20:21], 7, v[22:23]
	v_lshl_add_u64 v[18:19], s[10:11], 0, v[20:21]
	v_lshl_add_u64 v[18:19], v[0:1], 1, v[18:19]
	v_lshl_add_u64 v[26:27], v[18:19], 0, s[50:51]
	v_lshlrev_b64 v[18:19], 8, v[22:23]
	s_or_saveexec_b64 s[10:11], s[14:15]
	v_mov_b64_e32 v[24:25], v[0:1]
	s_xor_b64 exec, exec, s[10:11]
	v_lshl_add_u64 v[26:27], s[0:1], 0, v[18:19]
	v_ashrrev_i32_e32 v25, 31, v0
	v_mov_b32_e32 v24, v0
	v_lshl_add_u64 v[26:27], v[24:25], 1, v[26:27]
	s_or_b64 exec, exec, s[10:11]
	s_lshl_b32 s14, s19, 2
	s_add_u32 s0, s8, s20
	global_load_dwordx4 v[124:127], v[26:27], off
	v_lshlrev_b32_e32 v26, 3, v29
	s_addc_u32 s1, s9, 0
	v_ashrrev_i32_e32 v27, 31, v26
	s_add_u32 s0, s0, 0xeb00000
	v_lshlrev_b64 v[32:33], 1, v[26:27]
	v_add_u32_e32 v26, 0x800, v26
	s_addc_u32 s1, s1, 0
	v_ashrrev_i32_e32 v27, 31, v26
	v_lshl_add_u64 v[34:35], s[0:1], 0, v[32:33]
	v_lshlrev_b64 v[26:27], 1, v[26:27]
	v_lshl_add_u64 v[36:37], s[0:1], 0, v[26:27]
	global_load_dwordx4 v[132:135], v[34:35], off
	global_load_dwordx4 v[128:131], v[36:37], off
	v_mul_lo_u32 v8, v8, s31
	v_lshl_add_u32 v189, v2, 1, v8
	v_mul_lo_u32 v8, v16, s31
	v_lshl_add_u32 v190, v10, 1, v8
	v_mul_lo_u32 v8, v22, s31
	v_lshl_add_u32 v191, v24, 1, v8
	v_lshlrev_b32_e32 v8, 4, v29
	v_lshrrev_b32_e32 v16, 2, v29
	v_and_b32_e32 v8, 48, v8
	v_mad_u64_u32 v[164:165], s[0:1], v16, s36, v[8:9]
	v_lshrrev_b32_e32 v9, 2, v9
	v_mad_u64_u32 v[166:167], s[0:1], v9, s36, v[8:9]
	s_lshl_b32 s0, s18, 1
	s_or_b32 s15, s14, 3
	s_and_b32 s10, s0, 0x3e00000
	s_add_u32 s0, s10, 0xeb02000
	s_addc_u32 s1, 0, 0
	v_lshl_add_u64 v[168:169], s[0:1], 0, v[26:27]
	v_lshl_add_u64 v[170:171], s[0:1], 0, v[32:33]
	s_lshl_b32 s0, s16, 17
	s_and_b32 s0, s0, 0x300000
	s_or_b32 s0, s0, 0x1d868f00
	v_ashrrev_i32_e32 v17, 6, v29
	s_mov_b32 s1, 0
	s_add_u32 s10, s10, 0x8982000
	v_add_u32_e32 v17, s14, v17
	v_mov_b32_e32 v8, v2
	v_mov_b32_e32 v9, v1
	s_addc_u32 s11, 0, 0
	v_lshl_add_u64 v[4:5], s[0:1], 0, v[4:5]
	v_or_b32_e32 v188, 1, v17
	v_mov_b32_e32 v16, v10
	v_mov_b32_e32 v17, v1
	v_lshl_add_u64 v[12:13], s[0:1], 0, v[12:13]
	s_waitcnt vmcnt(24)
; template <int DQ, int DV, int NQT, bool SAMPLE>
; DEV void attn_item(const Params& p, int item, char* smem) {
;     ...
;   f32x4 o[DV / 16][NQT];
;   float mrun[NQT], lrun[NQT];
; #pragma unroll
;   for (int qt = 0; qt < NQT; qt++) {
;     mrun[qt] = -INFINITY;
;     lrun[qt] = 0.f;
; #pragma unroll
;     for (int d = 0; d < DV / 16; d++) o[d][qt] = (f32x4){0.f, 0.f, 0.f, 0.f};
;   }
;   u32x4 rk[NKC], rv[NVC];
;   auto gload = [&](int kt) {
; #pragma unroll
;     for (int i = 0; i < NKC; i++) {
;       const int c = tid + i * 256, row = c / CPR, col = (c % CPR) * 8;
;       const size_t key = (size_t)kt * 32 + row;
;       const u16* srcp = (col < D1) ? (K1 + key * ld1 + col) : (K2 + key * 64 + (col - D1));
;       rk[i] = *(const u32x4*)srcp;
;     }
; #pragma unroll
;     for (int i = 0; i < NVC; i++) {
;       const int c = tid + i * 256, row = c >> 2, kc = c & 3;
;       rv[i] = *(const u32x4*)(Vt + (size_t)kt * (DV * 32) + (row * 4 + kc) * 8);
;     }
;   };
;   auto swrite = [&]() {
; #pragma unroll
;     for (int i = 0; i < NKC; i++) {
;       const int c = tid + i * 256, row = c / CPR, col = (c % CPR) * 8;
;       *(u32x4*)(sK + row * KS + col) = rk[i];
;     }
; #pragma unroll
;     for (int i = 0; i < NVC; i++) {
;       const int c = tid + i * 256, row = c >> 2, kc = c & 3;
;       *(u32x4*)(sV + row * VS + kc * 8) = rv[i];
;     }
;   };
;   const float sc = 0.07216878364870322f * 1.4426950408889634f;
;   gload(0);
;   for (int kt = 0; kt < nkt; kt++) {
;     swrite();
;     __syncthreads();
;     if (kt + 1 < nkt) gload(kt + 1);
	v_lshl_add_u64 v[180:181], v[8:9], 1, v[4:5]
	v_lshl_add_u64 v[4:5], s[10:11], 0, v[6:7]
	v_lshlrev_b32_e32 v23, 3, v30
	v_lshl_add_u64 v[20:21], s[0:1], 0, v[20:21]
	v_lshl_add_u64 v[18:19], s[10:11], 0, v[18:19]
	v_lshl_add_u64 v[176:177], v[16:17], 1, v[12:13]
	v_lshl_add_u64 v[12:13], s[10:11], 0, v[14:15]
	v_lshl_add_u64 v[182:183], v[2:3], 1, v[4:5]
	v_mov_b32_e32 v2, v1
	v_mov_b32_e32 v3, v1
	v_lshlrev_b32_e32 v186, 1, v23
	v_lshlrev_b32_e32 v165, 2, v30
	v_mul_u32_u24_e32 v187, 0x190, v28
	v_mad_u32_u24 v167, v28, s36, v23
	v_lshl_add_u64 v[172:173], v[0:1], 1, v[20:21]
	v_lshl_add_u64 v[174:175], v[24:25], 1, v[18:19]
	v_lshl_add_u64 v[178:179], v[10:11], 1, v[12:13]
	v_mov_b32_e32 v0, v1
	v_mov_b64_e32 v[6:7], v[2:3]
	v_mov_b64_e32 v[38:39], v[2:3]
	v_mov_b64_e32 v[10:11], v[2:3]
	v_mov_b64_e32 v[42:43], v[2:3]
	v_mov_b64_e32 v[14:15], v[2:3]
	v_mov_b64_e32 v[46:47], v[2:3]
	v_mov_b64_e32 v[18:19], v[2:3]
	v_mov_b64_e32 v[50:51], v[2:3]
	v_mov_b64_e32 v[22:23], v[2:3]
	v_mov_b64_e32 v[54:55], v[2:3]
	v_mov_b64_e32 v[26:27], v[2:3]
	v_mov_b64_e32 v[58:59], v[2:3]
	v_mov_b64_e32 v[30:31], v[2:3]
	v_mov_b64_e32 v[62:63], v[2:3]
	v_mov_b64_e32 v[34:35], v[2:3]
	v_mov_b64_e32 v[66:67], v[2:3]
	v_ashrrev_i32_e32 v153, 31, v152
	v_ashrrev_i32_e32 v163, 31, v162
	v_add_u32_e32 v184, 0x500, v167
	v_mov_b32_e32 v161, 0
	s_waitcnt vmcnt(23)
	v_mov_b32_e32 v185, 0xff800000
	v_mov_b64_e32 v[4:5], v[0:1]
	v_mov_b64_e32 v[36:37], v[0:1]
	v_mov_b64_e32 v[8:9], v[0:1]
	v_mov_b64_e32 v[40:41], v[0:1]
	v_mov_b64_e32 v[12:13], v[0:1]
	v_mov_b64_e32 v[44:45], v[0:1]
	v_mov_b64_e32 v[16:17], v[0:1]
	v_mov_b64_e32 v[48:49], v[0:1]
	v_mov_b64_e32 v[20:21], v[0:1]
	v_mov_b64_e32 v[52:53], v[0:1]
	v_mov_b64_e32 v[24:25], v[0:1]
	v_mov_b64_e32 v[56:57], v[0:1]
	v_mov_b64_e32 v[28:29], v[0:1]
	v_mov_b64_e32 v[60:61], v[0:1]
	v_mov_b64_e32 v[32:33], v[0:1]
	v_mov_b64_e32 v[64:65], v[0:1]
	v_mov_b32_e32 v2, 0xff800000
	v_mov_b32_e32 v0, 0
	v_mov_b32_e32 v3, 0x2000
	v_mov_b32_e32 v192, 0x1000
	v_cndmask_b32_e64 v183, v181, v183, s[2:3]
	v_cndmask_b32_e64 v182, v180, v182, s[2:3]
	v_lshl_add_u64 v[182:183], s[8:9], 0, v[182:183]
	v_cndmask_b32_e64 v180, v192, v3, s[2:3]
	v_mov_b32_e32 v181, 0
	v_cndmask_b32_e64 v179, v177, v179, s[4:5]
	v_cndmask_b32_e64 v178, v176, v178, s[4:5]
	v_lshl_add_u64 v[178:179], s[8:9], 0, v[178:179]
	v_cndmask_b32_e64 v176, v192, v3, s[4:5]
	v_mov_b32_e32 v177, 0
	v_cndmask_b32_e64 v175, v173, v175, s[6:7]
	v_cndmask_b32_e64 v174, v172, v174, s[6:7]
	v_lshl_add_u64 v[174:175], s[8:9], 0, v[174:175]
	v_cndmask_b32_e64 v172, v192, v3, s[6:7]
	v_mov_b32_e32 v173, 0
	v_lshl_add_u64 v[170:171], s[8:9], 0, v[170:171]
	v_lshl_add_u64 v[168:169], s[8:9], 0, v[168:169]
	s_branch .LBB0_464

; DEV int tidx() { int t = threadIdx.x; asm volatile("" : "+v"(t)); return t; }
; #define ctr ((int*)(wsp(p) + W_CTR))
; DEV void phase_scan(const Params& p, int layer, int* ctr, char* smem) {
;   int* sitem = (int*)(smem + 78848);
;   for (;;) {
;     __syncthreads();
;     if (tidx() == 0) *sitem = atomicAdd(ctr, 1);
;     __syncthreads();
;     const int item = __builtin_amdgcn_readfirstlane(*sitem);
.LBB0_1137:
	s_or_b64 exec, exec, s[0:1]
	s_mov_b64 s[0:1], s[62:63]
	s_barrier
	v_readlane_b32 s2, v255, 30
	v_readlane_b32 s3, v255, 31
	s_add_u32 s0, s0, s2
	s_addc_u32 s1, s1, s3
	s_add_u32 s4, s0, 0x2720004
	v_readlane_b32 s0, v254, 58
	s_addc_u32 s5, s1, 0
	s_lshl_b32 s8, s0, 7
	s_lshl_b32 s9, s0, 5
	s_cmp_lt_u32 s52, 0x80
	s_cselect_b32 s100, 1, 0
	s_branch .LBB0_1140

; DEV int tidx() { int t = threadIdx.x; asm volatile("" : "+v"(t)); return t; }
; #define ctr ((int*)(wsp(p) + W_CTR))
; DEV void phase_scan(const Params& p, int layer, int* ctr, char* smem) {
;     ...
;   for (;;) {
;     __syncthreads();
;     if (tidx() == 0) *sitem = atomicAdd(ctr, 1);
;     __syncthreads();
;     const int item = __builtin_amdgcn_readfirstlane(*sitem);
.LBB0_1140:
	v_mov_b32_e32 v0, v157
	s_barrier
	s_cmp_eq_u32 s100, 0
	s_cbranch_scc1 .Lsc_fetch
	s_mov_b32 s100, 0
	s_and_b32 s2, s52, 7
	s_lshr_b32 s3, s52, 5
	s_lshl_b32 s3, s3, 3
	s_add_i32 s2, s2, s3
	s_lshl_b32 s2, s2, 2
	s_bfe_u32 s3, s52, 0x20003
	s_add_i32 s2, s2, s3
	s_mov_b64 s[0:1], -1
	s_branch .Lsc_decode
.Lsc_fetch:
	s_nop 0
	v_cmp_eq_u32_e32 vcc, 0, v0
	s_and_saveexec_b64 s[0:1], vcc
	s_cbranch_execz .LBB0_1144
	s_mov_b64 s[6:7], exec
	v_mbcnt_lo_u32_b32 v0, s6, 0
	v_mbcnt_hi_u32_b32 v0, s7, v0
	v_cmp_eq_u32_e32 vcc, 0, v0
	s_and_saveexec_b64 s[2:3], vcc
	s_cbranch_execz .LBB0_1143
	s_bcnt1_i32_b64 s6, s[6:7]
	v_mov_b32_e32 v2, s6
	global_atomic_add v2, v1, v2, s[4:5] sc0

; DEV int tidx() { int t = threadIdx.x; asm volatile("" : "+v"(t)); return t; }
; #define ctr ((int*)(wsp(p) + W_CTR))
; DEV void gdn_scan_item(const Params& p, int layer, int item, char* smem) {
;     ...
;   const bool smp = item >= 128;
;   const int it = smp ? item - 128 : item;
;   const int b = it >> 5, h = (it >> 2) & 7, s = it & 3;
;   const int nch = smp ? 1 : 128;
;   f32x4 Sacc[2][2];
; #pragma unroll
;   for (int dt = 0; dt < 2; dt++)
; #pragma unroll
;     for (int kk = 0; kk < 2; kk++) {
;       if (smp) {
;         const int k = (2 * w + kk) * 16 + fr, dv = s * 32 + dt * 16 + fq * 4;
;         const float4 v = *(const float4*)(p.in[3] + ((size_t)((layer * 16 + b) * 8 + h) * 128 + k) * 128 + dv);
; DEV void phase_scan(const Params& p, int layer, int* ctr, char* smem) {
;     ...
;     __syncthreads();
;     if (tidx() == 0) *sitem = atomicAdd(ctr, 1);
;     __syncthreads();
;     const int item = __builtin_amdgcn_readfirstlane(*sitem);
;     if (item >= 128 + 512) break;
.LBB0_1144:
	s_or_b64 exec, exec, s[0:1]
	s_waitcnt lgkmcnt(0)
	s_barrier
	ds_read_b32 v0, v202
	s_mov_b64 s[0:1], -1
	s_waitcnt lgkmcnt(0)
	v_readfirstlane_b32 s2, v0
	s_addk_i32 s2, 0x80
.Lsc_decode:
	s_cmpk_gt_i32 s2, 0x27f
	s_cbranch_scc1 .LBB0_1139
	s_cmpk_lt_i32 s2, 0x80
	s_cselect_b64 s[12:13], -1, 0
	s_add_i32 s3, s2, 0xffffff80
	s_cmpk_gt_i32 s2, 0x7f
	s_cselect_b64 s[0:1], -1, 0
	s_and_b64 s[6:7], s[0:1], exec
	s_cselect_b32 s2, s3, s2
	s_ashr_i32 s14, s2, 5
	s_lshl_b32 s27, s14, 3
	s_bfe_u32 s26, s2, 0x30002
	s_and_b32 s24, s2, 3
	s_add_i32 s2, s27, s8
	v_mov_b32_e32 v18, v157
	s_or_b32 s2, s2, s26
	s_ashr_i32 s3, s2, 31
	s_waitcnt vmcnt(22)
	v_bfe_u32 v74, v18, 4, 2
	v_lshlrev_b32_e32 v77, 2, v74
	s_lshl_b64 s[6:7], s[2:3], 16
	v_ashrrev_i32_e32 v76, 6, v18
	v_and_b32_e32 v75, 15, v18
	v_lshl_or_b32 v0, s24, 5, v77
	s_add_u32 s2, s78, s6
	v_lshl_or_b32 v162, v76, 5, v75
	s_addc_u32 s3, s79, s7
	v_lshlrev_b32_e32 v0, 2, v0
	s_mov_b64 s[10:11], s[62:63]
	v_lshl_add_u64 v[14:15], s[2:3], 0, v[0:1]
	s_and_b64 vcc, exec, s[12:13]
	v_ashrrev_i32_e32 v163, 31, v162
	s_cbranch_vccnz .LBB0_1147
	v_lshlrev_b64 v[2:3], 9, v[162:163]
	v_lshl_add_u64 v[2:3], v[14:15], 0, v[2:3]
	global_load_dwordx4 v[2:5], v[2:3], off
	s_branch .LBB0_1148

; __global__ void __launch_bounds__(256, 2) fwd_megakernel(Params p) {
;   __shared__ __attribute__((aligned(16))) char smem[SMEM_BYTES];
	.amdhsa_kernel _Z14fwd_megakernel6Params
		.amdhsa_group_segment_fixed_size 78912
		.amdhsa_private_segment_fixed_size 0
		.amdhsa_kernarg_size 464
		.amdhsa_user_sgpr_count 2
		.amdhsa_user_sgpr_dispatch_ptr 0
		.amdhsa_user_sgpr_queue_ptr 0
		.amdhsa_user_sgpr_kernarg_segment_ptr 1
		.amdhsa_user_sgpr_dispatch_id 0
		.amdhsa_user_sgpr_kernarg_preload_length 0
		.amdhsa_user_sgpr_kernarg_preload_offset 0
		.amdhsa_user_sgpr_private_segment_size 0
		.amdhsa_uses_dynamic_stack 0
		.amdhsa_enable_private_segment 0
		.amdhsa_system_sgpr_workgroup_id_x 1
		.amdhsa_system_sgpr_workgroup_id_y 0
		.amdhsa_system_sgpr_workgroup_id_z 0
		.amdhsa_system_sgpr_workgroup_info 0
		.amdhsa_system_vgpr_workitem_id 2
		.amdhsa_next_free_vgpr 256
		.amdhsa_next_free_sgpr 101
		.amdhsa_accum_offset 256
		.amdhsa_reserve_vcc 1
		.amdhsa_float_round_mode_32 0
		.amdhsa_float_round_mode_16_64 0
		.amdhsa_float_denorm_mode_32 3
		.amdhsa_float_denorm_mode_16_64 3
		.amdhsa_dx10_clamp 1
		.amdhsa_ieee_mode 1
		.amdhsa_fp16_overflow 0
		.amdhsa_tg_split 0
		.amdhsa_exception_fp_ieee_invalid_op 0
		.amdhsa_exception_fp_denorm_src 0
		.amdhsa_exception_fp_ieee_div_zero 0
		.amdhsa_exception_fp_ieee_overflow 0
		.amdhsa_exception_fp_ieee_underflow 0
		.amdhsa_exception_fp_ieee_inexact 0
		.amdhsa_exception_int_div_zero 0
	.end_amdhsa_kernel

; __global__ void __launch_bounds__(256, 2) fwd_megakernel(Params p) {
;   __shared__ __attribute__((aligned(16))) char smem[SMEM_BYTES];
amdhsa.kernels:
  - .agpr_count:     0
    .args:
      - .offset:         0
        .size:           208
        .value_kind:     by_value
      - .offset:         208
        .size:           4
        .value_kind:     hidden_block_count_x
      - .offset:         212
        .size:           4
        .value_kind:     hidden_block_count_y
      - .offset:         216
        .size:           4
        .value_kind:     hidden_block_count_z
      - .offset:         220
        .size:           2
        .value_kind:     hidden_group_size_x
      - .offset:         222
        .size:           2
        .value_kind:     hidden_group_size_y
      - .offset:         224
        .size:           2
        .value_kind:     hidden_group_size_z
      - .offset:         226
        .size:           2
        .value_kind:     hidden_remainder_x
      - .offset:         228
        .size:           2
        .value_kind:     hidden_remainder_y
      - .offset:         230
        .size:           2
        .value_kind:     hidden_remainder_z
      - .offset:         248
        .size:           8
        .value_kind:     hidden_global_offset_x
      - .offset:         256
        .size:           8
        .value_kind:     hidden_global_offset_y
      - .offset:         264
        .size:           8
        .value_kind:     hidden_global_offset_z
      - .offset:         272
        .size:           2
        .value_kind:     hidden_grid_dims
      - .offset:         296
        .size:           8
        .value_kind:     hidden_multigrid_sync_arg
    .group_segment_fixed_size: 78912
    .kernarg_segment_align: 8
    .kernarg_segment_size: 464
    .language:       OpenCL C
    .language_version:
      - 2
      - 0
    .max_flat_workgroup_size: 256
    .name:           _Z14fwd_megakernel6Params
    .private_segment_fixed_size: 0
    .sgpr_count:     107
    .sgpr_spill_count: 120
    .symbol:         _Z14fwd_megakernel6Params.kd
    .uniform_work_group_size: 1
    .uses_dynamic_stack: false
    .vgpr_count:     256
    .vgpr_spill_count: 0
    .wavefront_size: 64
